# norm2 chunk preamble: the 12 gain/scale/shift vector loads issued together instead of four load-wait rounds (stacked on v139)
# speedup vs baseline: 1.0033x; 1.0033x over previous
.LBB0_753:
	s_ashr_i32 s5, s4, 31
	s_lshl_b64 s[6:7], s[4:5], 11
	v_lshl_add_u64 v[40:41], v[36:37], 0, s[6:7]
	s_lshl_b64 s[6:7], s[4:5], 12
	s_cmpk_gt_i32 s8, 0x3ff
	v_lshl_add_u64 v[42:43], v[38:39], 0, s[6:7]
	s_cselect_b32 s5, 0x6000, 0
	v_readlane_b32 s6, v254, 45
	v_readlane_b32 s7, v254, 46
	s_add_u32 s6, s6, s5
	s_addc_u32 s7, s7, 0
	v_lshl_add_u64 v[8:9], v[32:33], 2, s[6:7]
	s_mov_b64 s[6:7], 0x4000
	v_lshl_add_u64 v[16:17], v[8:9], 0, s[6:7]
	s_mov_b64 s[6:7], 0x3000
	v_lshl_add_u64 v[20:21], v[8:9], 0, s[6:7]
	s_mov_b64 s[6:7], 0
	s_mov_b64 s[10:11], 0x1000
	s_mov_b32 s5, 0x3300000
	global_load_dwordx4 v[68:71], v[34:35], off
	global_load_dwordx4 v[84:87], v[16:17], off
	global_load_dwordx4 v[72:75], v[34:35], off offset:1024
	global_load_dwordx4 v[88:91], v[16:17], off offset:1024
	global_load_dwordx4 v[76:79], v[34:35], off offset:2048
	global_load_dwordx4 v[92:95], v[16:17], off offset:2048
	global_load_dwordx4 v[80:83], v[34:35], off offset:3072
	global_load_dwordx4 v[96:99], v[16:17], off offset:3072
	global_load_dwordx4 v[0:3], v[20:21], off
	global_load_dwordx4 v[4:7], v[20:21], off offset:1024
	global_load_dwordx4 v[8:11], v[20:21], off offset:2048
	global_load_dwordx4 v[12:15], v[20:21], off offset:3072
	s_waitcnt vmcnt(4)
	v_pk_add_f32 v[84:85], v[84:85], 1.0 op_sel_hi:[1,0]
	v_pk_add_f32 v[86:87], v[86:87], 1.0 op_sel_hi:[1,0]
	v_pk_add_f32 v[88:89], v[88:89], 1.0 op_sel_hi:[1,0]
	v_pk_add_f32 v[90:91], v[90:91], 1.0 op_sel_hi:[1,0]
	v_pk_add_f32 v[92:93], v[92:93], 1.0 op_sel_hi:[1,0]
	v_pk_add_f32 v[94:95], v[94:95], 1.0 op_sel_hi:[1,0]
	v_pk_add_f32 v[96:97], v[96:97], 1.0 op_sel_hi:[1,0]
	v_pk_add_f32 v[98:99], v[98:99], 1.0 op_sel_hi:[1,0]
	v_pk_mul_f32 v[46:47], v[68:69], v[84:85]
	v_pk_mul_f32 v[44:45], v[70:71], v[86:87]
	v_pk_mul_f32 v[48:49], v[74:75], v[90:91]
	v_pk_mul_f32 v[50:51], v[72:73], v[88:89]
	v_pk_mul_f32 v[52:53], v[78:79], v[94:95]
	v_pk_mul_f32 v[54:55], v[76:77], v[92:93]
	v_pk_mul_f32 v[56:57], v[82:83], v[98:99]
	v_pk_mul_f32 v[58:59], v[80:81], v[96:97]
